# FFN-out paired tiles (two 128x128 tiles share the weight tile) with double-buffered weight stage, paired residual epilogue
# speedup vs baseline: 1.0079x; 1.0059x over previous
; DI int lat_tile(int i) { return (i >> 4) * 18 + 2 + (i & 15); }
; template <int KSEL> DI void run_phase(const Params& p, int ph, char* lds) {
;     ...
;   const int l = (ph - 1) / 9, kq = (ph - 1) % 9, k = kq < 2 ? kq : kq + 1;
;   const bool last = (l == 1);
;   const int lb = ((G & 7) == 0) ? (bid & 7) * (G >> 3) + (bid >> 3) : bid;
;   if (KSEL >= 0 && KSEL != 10 && k != (KSEL == 11 ? 4 : KSEL)) return;
;   switch (k) {
;     ...
;     case 9: {
;       EpiRes e{&p, l, false, 5 * 1024};
;       const int nm = last ? 128 : 144;
;       for (int i = 0, tm, tn; xcd_tile(bid, G, i, nm, 8, tm, tn); ++i) gemm_tile(p.ACT, 2816, p.Wffo, 2816, 2816, (last ? lat_tile(tm) : tm) * 128, tn * 128, lds, e);
.LBB0_62:
	v_mov_b32_e32 v114, v138
	s_cmp_lg_u32 s77, 0
	v_writelane_b32 v250, s77, 3
	s_cbranch_scc0 .LBB0_69
	s_add_i32 s0, s77, -1
	s_mul_hi_i32 s1, s0, 0x38e38e39
	s_lshr_b32 s2, s1, 31
	s_ashr_i32 s1, s1, 1
	s_add_i32 s49, s1, s2
	s_mul_i32 s82, s49, 9
	s_sub_i32 s2, s0, s82
	s_cmp_gt_i32 s2, 1
	s_cselect_b64 s[0:1], -1, 0
	s_cmp_lg_u64 s[0:1], 0
	s_addc_u32 s44, s2, 0
	s_add_i32 s0, s77, -10
	s_cmp_lt_u32 s0, 9
	s_cselect_b64 s[0:1], -1, 0
	v_writelane_b32 v250, s0, 4
	s_mov_b64 s[54:55], s[80:81]
	v_and_b32_e32 v115, 63, v114
	v_writelane_b32 v250, s1, 5
	v_ashrrev_i32_e32 v158, 6, v114
	s_cmp_lt_i32 s44, 5
	s_mov_b64 s[0:1], -1
	s_cbranch_scc1 .LBB0_357
	s_cmp_lt_i32 s44, 7
	s_cbranch_scc1 .LBB0_250
	s_cmp_lt_i32 s44, 8
	s_cbranch_scc1 .LBB0_228
	s_cmp_lt_i32 s44, 9
	s_cbranch_scc1 .LBB0_118
	s_cmp_eq_u32 s44, 9
	s_cbranch_scc0 .LBB0_117
	v_readlane_b32 s0, v250, 4
	v_readlane_b32 s1, v250, 5
	s_and_b64 s[0:1], s[0:1], exec
	s_movk_i32 s0, 0x40
	s_cselect_b32 s26, s0, 0x48
	v_cvt_f32_ubyte0_e32 v1, s26
	v_rcp_iflag_f32_e32 v1, v1
	s_lshr_b32 s37, s26, 3
	v_readlane_b32 s1, v251, 50
	s_sub_i32 s0, 0, s26
	v_mul_f32_e32 v1, 0x4f7ffffe, v1
	v_cvt_u32_f32_e32 v1, v1
	s_mul_i32 s37, s37, s1
	s_mov_b32 s27, 0
	s_lshl_b32 s36, s26, 3
	v_readfirstlane_b32 s1, v1
	s_mul_i32 s0, s0, s1
	s_mul_hi_u32 s0, s1, s0
	s_add_i32 s38, s1, s0
	s_branch .LBB0_72

; DI int opaque_tid() { int t = threadIdx.x; asm volatile("" : "+v"(t)); return t; }
; DI int lat_tile(int i) { return (i >> 4) * 18 + 2 + (i & 15); }
; template <class Epi>
; DI void gemm_tile(const bf16_t* __restrict__ A, int lda, const bf16_t* __restrict__ Bt, int ldb, int K, int row0, int col0, char* lds, const Epi& epi) {
;   const int tid = opaque_tid(), lane = tid & 63, wid = tid >> 6, wr = wid >> 1, wc = wid & 1, fr = lane & 15, fq = lane >> 4;
;   const bf16_t* ag[4];
;   const bf16_t* bg[4];
; #pragma unroll
;   for (int i = 0; i < 4; ++i) {
;     const int id = i * 256 + tid, r = id >> 3, cp = id & 7, c = cp ^ ((r >> 1) & 7);
;     ag[i] = A + (size_t)(row0 + r) * lda + c * 8;
;     bg[i] = Bt + (size_t)(col0 + r) * ldb + c * 8;
;   }
; template <int KSEL> DI void run_phase(const Params& p, int ph, char* lds) {
;     ...
;       for (int i = 0, tm, tn; xcd_tile(bid, G, i, nm, 8, tm, tn); ++i) gemm_tile(p.ACT, 2816, p.Wffo, 2816, 2816, (last ? lat_tile(tm) : tm) * 128, tn * 128, lds, e);
.LBB0_81:
	v_readlane_b32 s0, v250, 4
	v_readlane_b32 s1, v250, 5
	s_andn2_b64 vcc, exec, s[0:1]
	s_lshl_b32 s0, s39, 1
	s_cbranch_vccnz .LBB0_83
	s_lshl_b32 s1, s39, 1
	s_ashr_i32 s0, s1, 4
	s_mul_i32 s0, s0, 18
	s_and_b32 s1, s1, 15
	s_add_i32 s0, s1, s0
	s_add_i32 s0, s0, 2
.LBB0_83:
	v_mov_b32_e32 v34, v138
	v_readlane_b32 s4, v253, 26
	v_lshrrev_b32_e32 v35, 4, v34
	v_xor_b32_e32 v2, v35, v34
	v_lshlrev_b32_e32 v2, 4, v2
	v_and_b32_e32 v110, 0x70, v2
	v_readlane_b32 s5, v253, 27
	v_readlane_b32 s6, v253, 28
	v_readlane_b32 s7, v253, 29
	v_readlane_b32 s8, v253, 30
	v_readlane_b32 s9, v253, 31
	v_readlane_b32 s10, v253, 32
	v_readlane_b32 s11, v253, 33
	v_add_u32_e32 v14, 0x100, v34
	v_add_u32_e32 v22, 0x200, v34
	v_lshl_add_u64 v[2:3], s[10:11], 0, v[110:111]
	v_readlane_b32 s4, v253, 36
	v_add_u32_e32 v30, 0x300, v34
	s_lshl_b32 s3, s0, 7
	s_lshl_b32 s2, s40, 7
	v_readlane_b32 s6, v253, 38
	v_readlane_b32 s7, v253, 39
	v_ashrrev_i32_e32 v10, 3, v34
	v_ashrrev_i32_e32 v18, 3, v14
	v_ashrrev_i32_e32 v26, 3, v22
	v_ashrrev_i32_e32 v32, 3, v30
	v_lshl_add_u64 v[4:5], s[6:7], 0, v[110:111]
	v_add_u32_e32 v8, s3, v10
	s_movk_i32 s4, 0x1600
	v_add_u32_e32 v12, s2, v10
	v_add_u32_e32 v16, s3, v18
	v_add_u32_e32 v20, s2, v18
	v_add_u32_e32 v24, s3, v26
	v_add_u32_e32 v28, s2, v26
	v_add_u32_e32 v33, s3, v32
	v_add_u32_e32 v36, s2, v32
	v_mad_i64_i32 v[6:7], s[0:1], v8, s4, 0
	v_mad_i64_i32 v[8:9], s[0:1], v8, s4, v[2:3]
	v_mad_i64_i32 v[10:11], s[0:1], v12, s4, 0
	v_mad_i64_i32 v[12:13], s[0:1], v12, s4, v[4:5]
	v_mad_i64_i32 v[14:15], s[0:1], v16, s4, 0
	v_mad_i64_i32 v[16:17], s[0:1], v16, s4, v[2:3]
	v_mad_i64_i32 v[18:19], s[0:1], v20, s4, 0
	v_mad_i64_i32 v[20:21], s[0:1], v20, s4, v[4:5]
	v_mad_i64_i32 v[22:23], s[0:1], v24, s4, 0
	v_mad_i64_i32 v[24:25], s[0:1], v24, s4, v[2:3]
	v_mad_i64_i32 v[26:27], s[0:1], v28, s4, 0
	v_mad_i64_i32 v[28:29], s[0:1], v28, s4, v[4:5]
	v_mad_i64_i32 v[30:31], s[0:1], v33, s4, 0
	v_mad_i64_i32 v[2:3], s[0:1], v33, s4, v[2:3]
	v_mad_i64_i32 v[32:33], s[0:1], v36, s4, 0
	v_mad_i64_i32 v[4:5], s[0:1], v36, s4, v[4:5]
	s_waitcnt vmcnt(7)
	v_lshlrev_b32_e32 v90, 4, v34
	s_nop 0
	v_readfirstlane_b32 s0, v90
	s_mov_b32 m0, s0
	s_barrier
; #define LAS __attribute__((address_space(3)))
; template <class Epi>
; DI void gemm_tile(const bf16_t* __restrict__ A, int lda, const bf16_t* __restrict__ Bt, int ldb, int K, int row0, int col0, char* lds, const Epi& epi) {
;     ...
;   f32x4 acc[4][4];
; #pragma unroll
;   for (int m = 0; m < 4; ++m)
; #pragma unroll
;     for (int n = 0; n < 4; ++n) acc[m][n] = (f32x4){0.f, 0.f, 0.f, 0.f};
;   const int KT = K >> 6;
;   auto stage_a = [&](int kt, int buf) {
;     char* sa = lds + buf * 32768;
; #pragma unroll
;     for (int i = 0; i < 4; ++i)
;       __builtin_amdgcn_global_load_lds((const void __attribute__((address_space(1)))*)(ag[i] + kt * 64), (void LAS*)(sa + (i * 256 + tid) * 16), 16, 0, 0);
;   };
;   auto stage_b = [&](int kt, int buf) {
;     char* sb = lds + buf * 32768 + 16384;
; #pragma unroll
;     for (int i = 0; i < 4; ++i)
;       __builtin_amdgcn_global_load_lds((const void __attribute__((address_space(1)))*)(bg[i] + kt * 64), (void LAS*)(sb + (i * 256 + tid) * 16), 16, 0, 0);
;   };
;   __syncthreads();
;   stage_a(0, 0); stage_b(0, 0);
;   const int swz = fr >> 1;
	global_load_lds_dwordx4 v[8:9], off
	v_add_u32_e32 v8, 0x1000, v90
	v_and_b32_e32 v87, 15, v34
	v_readfirstlane_b32 s0, v8
	v_add_u32_e32 v8, 0x2000, v90
	s_mov_b32 m0, s0
	v_readfirstlane_b32 s0, v8
	v_add_u32_e32 v8, 0x3000, v90
	global_load_lds_dwordx4 v[16:17], off
	s_mov_b32 m0, s0
	v_readfirstlane_b32 s0, v8
	global_load_lds_dwordx4 v[24:25], off
	s_mov_b32 m0, s0
	v_bfe_u32 v1, v34, 6, 1
	global_load_lds_dwordx4 v[2:3], off
	v_add_u32_e32 v2, 0x4000, v90
	v_ashrrev_i32_e32 v88, 7, v34
	v_readfirstlane_b32 s0, v2
	v_add_u32_e32 v2, 0x5000, v90
	s_mov_b32 m0, s0
	v_readfirstlane_b32 s0, v2
	v_add_u32_e32 v2, 0x6000, v90
	global_load_lds_dwordx4 v[12:13], off
	s_mov_b32 m0, s0
	v_readfirstlane_b32 s0, v2
	v_add_u32_e32 v2, 0x7000, v90
	global_load_lds_dwordx4 v[20:21], off
	s_mov_b32 m0, s0
	v_readfirstlane_b32 s0, v2
	global_load_lds_dwordx4 v[28:29], off
	s_mov_b32 m0, s0
	v_bfe_u32 v86, v34, 4, 2
	global_load_lds_dwordx4 v[4:5], off
	v_bfe_u32 v2, v34, 1, 3
	v_lshlrev_b32_e32 v3, 7, v87
	v_lshl_or_b32 v91, v88, 13, v3
	s_waitcnt vmcnt(0)
	v_lshl_or_b32 v93, v1, 13, v3
	v_bitop3_b32 v3, v86, v2, 4 bitop3:0x36
	v_bitop3_b32 v2, v35, v2, 3 bitop3:0x6c
	v_lshlrev_b32_e32 v92, 4, v2
	v_bitop3_b32 v2, v35, 7, v34 bitop3:0x48
	v_lshlrev_b32_e32 v2, 4, v2
	v_readlane_b32 s0, v253, 9
	v_or_b32_e32 v10, v10, v2
	v_readlane_b32 s1, v253, 10
	v_or_b32_e32 v18, v18, v2
	v_or_b32_e32 v26, v26, v2
	v_or_b32_e32 v32, v32, v2
	v_lshl_add_u64 v[66:67], s[0:1], 0, v[10:11]
	v_lshl_add_u64 v[68:69], s[0:1], 0, v[18:19]
	v_lshl_add_u64 v[70:71], s[0:1], 0, v[26:27]
	v_lshl_add_u64 v[72:73], s[0:1], 0, v[32:33]
	v_readlane_b32 s0, v253, 11
	v_or_b32_e32 v6, v6, v2
	v_readlane_b32 s1, v253, 12
	v_or_b32_e32 v14, v14, v2
	v_or_b32_e32 v22, v22, v2
	v_or_b32_e32 v30, v30, v2
	v_mov_b32_e32 v2, 0
	v_lshlrev_b32_e32 v89, 4, v3
	v_lshl_add_u64 v[74:75], s[0:1], 0, v[6:7]
	v_lshl_add_u64 v[76:77], s[0:1], 0, v[14:15]
	v_lshl_add_u64 v[78:79], s[0:1], 0, v[22:23]
	v_lshl_add_u64 v[80:81], s[0:1], 0, v[30:31]
	s_mov_b64 s[0:1], 0
	s_mov_b32 s28, 0x8000
	v_mov_b32_e32 v3, v2
	v_mov_b32_e32 v4, v2
	v_mov_b32_e32 v5, v2
	v_mov_b32_e32 v6, v2
	v_mov_b32_e32 v7, v2
	v_mov_b32_e32 v8, v2
	v_mov_b32_e32 v9, v2
	v_mov_b32_e32 v10, v2
	v_mov_b32_e32 v11, v2
	v_mov_b32_e32 v12, v2
	v_mov_b32_e32 v13, v2
	v_mov_b32_e32 v14, v2
	v_mov_b32_e32 v15, v2
	v_mov_b32_e32 v16, v2
	v_mov_b32_e32 v17, v2
	v_mov_b32_e32 v18, v2
	v_mov_b32_e32 v19, v2
	v_mov_b32_e32 v20, v2
	v_mov_b32_e32 v21, v2
	v_mov_b32_e32 v22, v2
	v_mov_b32_e32 v23, v2
	v_mov_b32_e32 v24, v2
	v_mov_b32_e32 v25, v2
	v_mov_b32_e32 v26, v2
	v_mov_b32_e32 v27, v2
	v_mov_b32_e32 v28, v2
	v_mov_b32_e32 v29, v2
	v_mov_b32_e32 v30, v2
	v_mov_b32_e32 v31, v2
	v_mov_b32_e32 v32, v2
	v_mov_b32_e32 v33, v2
	v_mov_b32_e32 v34, v2
	v_mov_b32_e32 v35, v2
	v_mov_b32_e32 v36, v2
	v_mov_b32_e32 v37, v2
	v_mov_b32_e32 v38, v2
	v_mov_b32_e32 v39, v2
	v_mov_b32_e32 v40, v2
	v_mov_b32_e32 v41, v2
	v_mov_b32_e32 v42, v2
	v_mov_b32_e32 v43, v2
	v_mov_b32_e32 v44, v2
	v_mov_b32_e32 v45, v2
	v_mov_b32_e32 v46, v2
	v_mov_b32_e32 v47, v2
	v_mov_b32_e32 v48, v2
	v_mov_b32_e32 v49, v2
	v_mov_b32_e32 v50, v2
	v_mov_b32_e32 v51, v2
	v_mov_b32_e32 v52, v2
	v_mov_b32_e32 v53, v2
	v_mov_b32_e32 v54, v2
	v_mov_b32_e32 v55, v2
	v_mov_b32_e32 v56, v2
	v_mov_b32_e32 v57, v2
	v_mov_b32_e32 v58, v2
	v_mov_b32_e32 v59, v2
	v_mov_b32_e32 v60, v2
	v_mov_b32_e32 v61, v2
	v_mov_b32_e32 v62, v2
	v_mov_b32_e32 v63, v2
	v_mov_b32_e32 v64, v2
	v_mov_b32_e32 v65, v2
	v_readlane_b32 s5, v253, 37
	v_readlane_b32 s8, v253, 40
	v_readlane_b32 s9, v253, 41
	v_readlane_b32 s10, v253, 42
	v_readlane_b32 s11, v253, 43
	v_readlane_b32 s12, v253, 44
	v_readlane_b32 s13, v253, 45
	v_readlane_b32 s14, v253, 46
	v_readlane_b32 s15, v253, 47
	v_readlane_b32 s16, v253, 48
	v_readlane_b32 s17, v253, 49
	v_readlane_b32 s18, v253, 50
	v_readlane_b32 s19, v253, 51
	v_mov_b32_e32 v162, 0
	v_mov_b32_e32 v163, 0
	v_mov_b32_e32 v164, 0
	v_mov_b32_e32 v165, 0
	v_mov_b32_e32 v166, 0
	v_mov_b32_e32 v167, 0
	v_mov_b32_e32 v168, 0
	v_mov_b32_e32 v169, 0
	v_mov_b32_e32 v170, 0
	v_mov_b32_e32 v171, 0
	v_mov_b32_e32 v172, 0
	v_mov_b32_e32 v173, 0
	v_mov_b32_e32 v174, 0
	v_mov_b32_e32 v175, 0
	v_mov_b32_e32 v176, 0
	v_mov_b32_e32 v177, 0
	v_mov_b32_e32 v178, 0
	v_mov_b32_e32 v179, 0
	v_mov_b32_e32 v180, 0
	v_mov_b32_e32 v181, 0
	v_mov_b32_e32 v182, 0
	v_mov_b32_e32 v183, 0
	v_mov_b32_e32 v184, 0
	v_mov_b32_e32 v185, 0
	v_mov_b32_e32 v186, 0
	v_mov_b32_e32 v187, 0
	v_mov_b32_e32 v188, 0
	v_mov_b32_e32 v189, 0
	v_mov_b32_e32 v190, 0
	v_mov_b32_e32 v191, 0
	v_mov_b32_e32 v192, 0
	v_mov_b32_e32 v193, 0
	v_mov_b32_e32 v194, 0
	v_mov_b32_e32 v195, 0
	v_mov_b32_e32 v196, 0
	v_mov_b32_e32 v197, 0
	v_mov_b32_e32 v198, 0
	v_mov_b32_e32 v199, 0
	v_mov_b32_e32 v200, 0
	v_mov_b32_e32 v201, 0
	v_mov_b32_e32 v202, 0
	v_mov_b32_e32 v203, 0
	v_mov_b32_e32 v204, 0
	v_mov_b32_e32 v205, 0
	v_mov_b32_e32 v206, 0
	v_mov_b32_e32 v207, 0
	v_mov_b32_e32 v208, 0
	v_mov_b32_e32 v209, 0
	v_mov_b32_e32 v210, 0
	v_mov_b32_e32 v211, 0
	v_mov_b32_e32 v212, 0
	v_mov_b32_e32 v213, 0
	v_mov_b32_e32 v214, 0
	v_mov_b32_e32 v215, 0
	v_mov_b32_e32 v216, 0
	v_mov_b32_e32 v217, 0
	v_mov_b32_e32 v218, 0
	v_mov_b32_e32 v219, 0
	v_mov_b32_e32 v220, 0
	v_mov_b32_e32 v221, 0
	v_mov_b32_e32 v222, 0
	v_mov_b32_e32 v223, 0
	v_mov_b32_e32 v224, 0
	v_mov_b32_e32 v225, 0
	v_readfirstlane_b32 s21, v90
	v_add_u32_e32 v242, v91, v92
	v_add_u32_e32 v243, v93, v92
	v_add_u32_e32 v244, v91, v89
	v_add_u32_e32 v245, v93, v89
	s_mov_b32 s0, 0xaff80
	s_mov_b32 s1, 0
	s_add_i32 m0, s21, 0x8000
	v_lshl_add_u64 v[82:83], v[74:75], 0, s[0:1]
	global_load_lds_dwordx4 v[82:83], off
	s_add_i32 m0, m0, 0x1000
	v_lshl_add_u64 v[82:83], v[76:77], 0, s[0:1]
	global_load_lds_dwordx4 v[82:83], off
	s_add_i32 m0, m0, 0x1000
	v_lshl_add_u64 v[82:83], v[78:79], 0, s[0:1]
	global_load_lds_dwordx4 v[82:83], off
	s_add_i32 m0, m0, 0x1000
	v_lshl_add_u64 v[82:83], v[80:81], 0, s[0:1]
	global_load_lds_dwordx4 v[82:83], off
	s_mov_b64 s[0:1], 0
	s_add_i32 m0, s21, 0xc000
	v_lshl_add_u64 v[82:83], v[66:67], 0, s[0:1]
	global_load_lds_dwordx4 v[82:83], off
	s_add_i32 m0, m0, 0x1000
	v_lshl_add_u64 v[82:83], v[68:69], 0, s[0:1]
	global_load_lds_dwordx4 v[82:83], off
	s_add_i32 m0, m0, 0x1000
	v_lshl_add_u64 v[82:83], v[70:71], 0, s[0:1]
	global_load_lds_dwordx4 v[82:83], off
	s_add_i32 m0, m0, 0x1000
	v_lshl_add_u64 v[82:83], v[72:73], 0, s[0:1]
	global_load_lds_dwordx4 v[82:83], off

; template <class Epi>
; DI void gemm_tile(const bf16_t* __restrict__ A, int lda, const bf16_t* __restrict__ Bt, int ldb, int K, int row0, int col0, char* lds, const Epi& epi) {
;     ...
;   for (int kt = 0; kt < KT; ++kt) {
;     asm volatile("s_waitcnt vmcnt(0)" ::: "memory");
;     __syncthreads();
;     const char* sa = lds + (kt & 1) * 32768 + (wr * 64 + fr) * 128;
;     const char* sb = lds + (kt & 1) * 32768 + 16384 + (wc * 64 + fr) * 128;
; #pragma unroll
;     for (int kk = 0; kk < 2; ++kk) {
;       if (kt + 1 < KT) { if (kk == 0) stage_a(kt + 1, (kt + 1) & 1); else stage_b(kt + 1, (kt + 1) & 1); }
;       bf16x8 a[4], b[4];
;       const int co = ((kk * 4 + fq) ^ swz) * 16;
; #pragma unroll
;       for (int m = 0; m < 4; ++m) a[m] = *(const bf16x8*)(sa + m * 2048 + co);
; #pragma unroll
;       for (int n = 0; n < 4; ++n) b[n] = *(const bf16x8*)(sb + n * 2048 + co);
; #pragma unroll
;       for (int m = 0; m < 4; ++m)
; #pragma unroll
;         for (int n = 0; n < 4; ++n) acc[m][n] = __builtin_amdgcn_mfma_f32_16x16x32_bf16(b[n], a[m], acc[m][n], 0, 0, 0);
;     }
;   }
.Lffo4_nob0:
	ds_read_b128 v[94:97], v242
	ds_read_b128 v[98:101], v242 offset:2048
	ds_read_b128 v[102:105], v242 offset:4096
	ds_read_b128 v[106:109], v242 offset:6144
	ds_read_b128 v[116:119], v243 offset:16384
	ds_read_b128 v[120:123], v243 offset:18432
	ds_read_b128 v[124:127], v243 offset:20480
	ds_read_b128 v[128:131], v243 offset:22528
	ds_read_b128 v[226:229], v242 offset:32768
	ds_read_b128 v[230:233], v242 offset:34816
	ds_read_b128 v[234:237], v242 offset:36864
	ds_read_b128 v[238:241], v242 offset:38912
	s_waitcnt lgkmcnt(0)
	v_mfma_f32_16x16x32_bf16 v[62:65], v[116:119], v[94:97], v[62:65]
	v_mfma_f32_16x16x32_bf16 v[58:61], v[120:123], v[94:97], v[58:61]
	v_mfma_f32_16x16x32_bf16 v[54:57], v[124:127], v[94:97], v[54:57]
	v_mfma_f32_16x16x32_bf16 v[50:53], v[128:131], v[94:97], v[50:53]
	v_mfma_f32_16x16x32_bf16 v[46:49], v[116:119], v[98:101], v[46:49]
	v_mfma_f32_16x16x32_bf16 v[42:45], v[120:123], v[98:101], v[42:45]
	v_mfma_f32_16x16x32_bf16 v[38:41], v[124:127], v[98:101], v[38:41]
	v_mfma_f32_16x16x32_bf16 v[34:37], v[128:131], v[98:101], v[34:37]
	v_mfma_f32_16x16x32_bf16 v[30:33], v[116:119], v[102:105], v[30:33]
	v_mfma_f32_16x16x32_bf16 v[26:29], v[120:123], v[102:105], v[26:29]
	v_mfma_f32_16x16x32_bf16 v[22:25], v[124:127], v[102:105], v[22:25]
	v_mfma_f32_16x16x32_bf16 v[18:21], v[128:131], v[102:105], v[18:21]
	v_mfma_f32_16x16x32_bf16 v[14:17], v[116:119], v[106:109], v[14:17]
	v_mfma_f32_16x16x32_bf16 v[10:13], v[120:123], v[106:109], v[10:13]
	v_mfma_f32_16x16x32_bf16 v[6:9], v[124:127], v[106:109], v[6:9]
	v_mfma_f32_16x16x32_bf16 v[2:5], v[128:131], v[106:109], v[2:5]
	v_mfma_f32_16x16x32_bf16 v[222:225], v[116:119], v[226:229], v[222:225]
	v_mfma_f32_16x16x32_bf16 v[218:221], v[120:123], v[226:229], v[218:221]
	v_mfma_f32_16x16x32_bf16 v[214:217], v[124:127], v[226:229], v[214:217]
	v_mfma_f32_16x16x32_bf16 v[210:213], v[128:131], v[226:229], v[210:213]
	v_mfma_f32_16x16x32_bf16 v[206:209], v[116:119], v[230:233], v[206:209]
	v_mfma_f32_16x16x32_bf16 v[202:205], v[120:123], v[230:233], v[202:205]
	v_mfma_f32_16x16x32_bf16 v[198:201], v[124:127], v[230:233], v[198:201]
	v_mfma_f32_16x16x32_bf16 v[194:197], v[128:131], v[230:233], v[194:197]
	v_mfma_f32_16x16x32_bf16 v[190:193], v[116:119], v[234:237], v[190:193]
	v_mfma_f32_16x16x32_bf16 v[186:189], v[120:123], v[234:237], v[186:189]
	v_mfma_f32_16x16x32_bf16 v[182:185], v[124:127], v[234:237], v[182:185]
	v_mfma_f32_16x16x32_bf16 v[178:181], v[128:131], v[234:237], v[178:181]
	v_mfma_f32_16x16x32_bf16 v[174:177], v[116:119], v[238:241], v[174:177]
	v_mfma_f32_16x16x32_bf16 v[170:173], v[120:123], v[238:241], v[170:173]
	v_mfma_f32_16x16x32_bf16 v[166:169], v[124:127], v[238:241], v[166:169]
	v_mfma_f32_16x16x32_bf16 v[162:165], v[128:131], v[238:241], v[162:165]
	ds_read_b128 v[94:97], v244
	ds_read_b128 v[98:101], v244 offset:2048
	ds_read_b128 v[102:105], v244 offset:4096
	ds_read_b128 v[106:109], v244 offset:6144
	ds_read_b128 v[116:119], v245 offset:16384
	ds_read_b128 v[120:123], v245 offset:18432
	ds_read_b128 v[124:127], v245 offset:20480
	ds_read_b128 v[128:131], v245 offset:22528
	ds_read_b128 v[226:229], v244 offset:32768
	ds_read_b128 v[230:233], v244 offset:34816
	ds_read_b128 v[234:237], v244 offset:36864
	ds_read_b128 v[238:241], v244 offset:38912
	s_waitcnt lgkmcnt(0)
	s_barrier
	s_mov_b32 m0, s21
	v_lshl_add_u64 v[82:83], v[74:75], 0, s[0:1]
	global_load_lds_dwordx4 v[82:83], off
	s_add_i32 m0, m0, 0x1000
	v_lshl_add_u64 v[84:85], v[76:77], 0, s[0:1]
	global_load_lds_dwordx4 v[84:85], off
	s_add_i32 m0, m0, 0x1000
	v_lshl_add_u64 v[82:83], v[78:79], 0, s[0:1]
	global_load_lds_dwordx4 v[82:83], off
	s_add_i32 m0, m0, 0x1000
	v_lshl_add_u64 v[84:85], v[80:81], 0, s[0:1]
	global_load_lds_dwordx4 v[84:85], off
	s_add_i32 m0, m0, 0x1000
	s_add_u32 s20, s0, 0xb0000
	s_add_i32 m0, s21, 0x8000
	v_add_co_u32_e32 v82, vcc, s20, v74
	v_addc_co_u32_e32 v83, vcc, 0, v75, vcc
	global_load_lds_dwordx4 v[82:83], off
	s_add_i32 m0, m0, 0x1000
	v_add_co_u32_e32 v84, vcc, s20, v76
	v_addc_co_u32_e32 v85, vcc, 0, v77, vcc
	global_load_lds_dwordx4 v[84:85], off
	s_add_i32 m0, m0, 0x1000
	v_add_co_u32_e32 v82, vcc, s20, v78
	v_addc_co_u32_e32 v83, vcc, 0, v79, vcc
	global_load_lds_dwordx4 v[82:83], off
	s_add_i32 m0, m0, 0x1000
	v_add_co_u32_e32 v84, vcc, s20, v80
	v_addc_co_u32_e32 v85, vcc, 0, v81, vcc
	global_load_lds_dwordx4 v[84:85], off
	v_mfma_f32_16x16x32_bf16 v[62:65], v[116:119], v[94:97], v[62:65]
	v_mfma_f32_16x16x32_bf16 v[58:61], v[120:123], v[94:97], v[58:61]
	v_mfma_f32_16x16x32_bf16 v[54:57], v[124:127], v[94:97], v[54:57]
	v_mfma_f32_16x16x32_bf16 v[50:53], v[128:131], v[94:97], v[50:53]
	v_mfma_f32_16x16x32_bf16 v[46:49], v[116:119], v[98:101], v[46:49]
	v_mfma_f32_16x16x32_bf16 v[42:45], v[120:123], v[98:101], v[42:45]
	v_mfma_f32_16x16x32_bf16 v[38:41], v[124:127], v[98:101], v[38:41]
	v_mfma_f32_16x16x32_bf16 v[34:37], v[128:131], v[98:101], v[34:37]
	v_mfma_f32_16x16x32_bf16 v[30:33], v[116:119], v[102:105], v[30:33]
	v_mfma_f32_16x16x32_bf16 v[26:29], v[120:123], v[102:105], v[26:29]
	v_mfma_f32_16x16x32_bf16 v[22:25], v[124:127], v[102:105], v[22:25]
	v_mfma_f32_16x16x32_bf16 v[18:21], v[128:131], v[102:105], v[18:21]
	v_mfma_f32_16x16x32_bf16 v[14:17], v[116:119], v[106:109], v[14:17]
	v_mfma_f32_16x16x32_bf16 v[10:13], v[120:123], v[106:109], v[10:13]
	v_mfma_f32_16x16x32_bf16 v[6:9], v[124:127], v[106:109], v[6:9]
	v_mfma_f32_16x16x32_bf16 v[2:5], v[128:131], v[106:109], v[2:5]
	v_mfma_f32_16x16x32_bf16 v[222:225], v[116:119], v[226:229], v[222:225]
	v_mfma_f32_16x16x32_bf16 v[218:221], v[120:123], v[226:229], v[218:221]
	v_mfma_f32_16x16x32_bf16 v[214:217], v[124:127], v[226:229], v[214:217]
	v_mfma_f32_16x16x32_bf16 v[210:213], v[128:131], v[226:229], v[210:213]
	v_mfma_f32_16x16x32_bf16 v[206:209], v[116:119], v[230:233], v[206:209]
	v_mfma_f32_16x16x32_bf16 v[202:205], v[120:123], v[230:233], v[202:205]
	v_mfma_f32_16x16x32_bf16 v[198:201], v[124:127], v[230:233], v[198:201]
	v_mfma_f32_16x16x32_bf16 v[194:197], v[128:131], v[230:233], v[194:197]
	v_mfma_f32_16x16x32_bf16 v[190:193], v[116:119], v[234:237], v[190:193]
	v_mfma_f32_16x16x32_bf16 v[186:189], v[120:123], v[234:237], v[186:189]
	v_mfma_f32_16x16x32_bf16 v[182:185], v[124:127], v[234:237], v[182:185]
	v_mfma_f32_16x16x32_bf16 v[178:181], v[128:131], v[234:237], v[178:181]
	v_mfma_f32_16x16x32_bf16 v[174:177], v[116:119], v[238:241], v[174:177]
	v_mfma_f32_16x16x32_bf16 v[170:173], v[120:123], v[238:241], v[170:173]
	v_mfma_f32_16x16x32_bf16 v[166:169], v[124:127], v[238:241], v[166:169]
	v_mfma_f32_16x16x32_bf16 v[162:165], v[128:131], v[238:241], v[162:165]
	s_add_u32 s0, s0, 0x80
	s_waitcnt vmcnt(0)
	s_barrier
; template <class Epi>
; DI void gemm_tile(const bf16_t* __restrict__ A, int lda, const bf16_t* __restrict__ Bt, int ldb, int K, int row0, int col0, char* lds, const Epi& epi) {
;     ...
;   for (int kt = 0; kt < KT; ++kt) {
;     asm volatile("s_waitcnt vmcnt(0)" ::: "memory");
;     __syncthreads();
;     const char* sa = lds + (kt & 1) * 32768 + (wr * 64 + fr) * 128;
;     const char* sb = lds + (kt & 1) * 32768 + 16384 + (wc * 64 + fr) * 128;
; #pragma unroll
;     for (int kk = 0; kk < 2; ++kk) {
;       if (kt + 1 < KT) { if (kk == 0) stage_a(kt + 1, (kt + 1) & 1); else stage_b(kt + 1, (kt + 1) & 1); }
;       bf16x8 a[4], b[4];
;       const int co = ((kk * 4 + fq) ^ swz) * 16;
; #pragma unroll
;       for (int m = 0; m < 4; ++m) a[m] = *(const bf16x8*)(sa + m * 2048 + co);
; #pragma unroll
;       for (int n = 0; n < 4; ++n) b[n] = *(const bf16x8*)(sb + n * 2048 + co);
; #pragma unroll
;       for (int m = 0; m < 4; ++m)
; #pragma unroll
;         for (int n = 0; n < 4; ++n) acc[m][n] = __builtin_amdgcn_mfma_f32_16x16x32_bf16(b[n], a[m], acc[m][n], 0, 0, 0);
;     }
;   }
	s_cmpk_eq_i32 s0, 0x1580
	s_cbranch_scc1 .Lffo4_nob1
	s_add_i32 m0, s21, 0x4000
	v_lshl_add_u64 v[82:83], v[66:67], 0, s[0:1]
	global_load_lds_dwordx4 v[82:83], off
	s_add_i32 m0, m0, 0x1000
	v_lshl_add_u64 v[84:85], v[68:69], 0, s[0:1]
	global_load_lds_dwordx4 v[84:85], off
	s_add_i32 m0, m0, 0x1000
	v_lshl_add_u64 v[82:83], v[70:71], 0, s[0:1]
	global_load_lds_dwordx4 v[82:83], off
	s_add_i32 m0, m0, 0x1000
	v_lshl_add_u64 v[84:85], v[72:73], 0, s[0:1]
	global_load_lds_dwordx4 v[84:85], off
.Lffo4_nob1:
	ds_read_b128 v[94:97], v242
	ds_read_b128 v[98:101], v242 offset:2048
	ds_read_b128 v[102:105], v242 offset:4096
	ds_read_b128 v[106:109], v242 offset:6144
	ds_read_b128 v[116:119], v243 offset:49152
	ds_read_b128 v[120:123], v243 offset:51200
	ds_read_b128 v[124:127], v243 offset:53248
	ds_read_b128 v[128:131], v243 offset:55296
	ds_read_b128 v[226:229], v242 offset:32768
	ds_read_b128 v[230:233], v242 offset:34816
	ds_read_b128 v[234:237], v242 offset:36864
	ds_read_b128 v[238:241], v242 offset:38912
	s_waitcnt lgkmcnt(0)
	v_mfma_f32_16x16x32_bf16 v[62:65], v[116:119], v[94:97], v[62:65]
	v_mfma_f32_16x16x32_bf16 v[58:61], v[120:123], v[94:97], v[58:61]
	v_mfma_f32_16x16x32_bf16 v[54:57], v[124:127], v[94:97], v[54:57]
	v_mfma_f32_16x16x32_bf16 v[50:53], v[128:131], v[94:97], v[50:53]
	v_mfma_f32_16x16x32_bf16 v[46:49], v[116:119], v[98:101], v[46:49]
	v_mfma_f32_16x16x32_bf16 v[42:45], v[120:123], v[98:101], v[42:45]
	v_mfma_f32_16x16x32_bf16 v[38:41], v[124:127], v[98:101], v[38:41]
	v_mfma_f32_16x16x32_bf16 v[34:37], v[128:131], v[98:101], v[34:37]
	v_mfma_f32_16x16x32_bf16 v[30:33], v[116:119], v[102:105], v[30:33]
	v_mfma_f32_16x16x32_bf16 v[26:29], v[120:123], v[102:105], v[26:29]
	v_mfma_f32_16x16x32_bf16 v[22:25], v[124:127], v[102:105], v[22:25]
	v_mfma_f32_16x16x32_bf16 v[18:21], v[128:131], v[102:105], v[18:21]
	v_mfma_f32_16x16x32_bf16 v[14:17], v[116:119], v[106:109], v[14:17]
	v_mfma_f32_16x16x32_bf16 v[10:13], v[120:123], v[106:109], v[10:13]
	v_mfma_f32_16x16x32_bf16 v[6:9], v[124:127], v[106:109], v[6:9]
	v_mfma_f32_16x16x32_bf16 v[2:5], v[128:131], v[106:109], v[2:5]
	v_mfma_f32_16x16x32_bf16 v[222:225], v[116:119], v[226:229], v[222:225]
	v_mfma_f32_16x16x32_bf16 v[218:221], v[120:123], v[226:229], v[218:221]
	v_mfma_f32_16x16x32_bf16 v[214:217], v[124:127], v[226:229], v[214:217]
	v_mfma_f32_16x16x32_bf16 v[210:213], v[128:131], v[226:229], v[210:213]
	v_mfma_f32_16x16x32_bf16 v[206:209], v[116:119], v[230:233], v[206:209]
	v_mfma_f32_16x16x32_bf16 v[202:205], v[120:123], v[230:233], v[202:205]
	v_mfma_f32_16x16x32_bf16 v[198:201], v[124:127], v[230:233], v[198:201]
	v_mfma_f32_16x16x32_bf16 v[194:197], v[128:131], v[230:233], v[194:197]
	v_mfma_f32_16x16x32_bf16 v[190:193], v[116:119], v[234:237], v[190:193]
	v_mfma_f32_16x16x32_bf16 v[186:189], v[120:123], v[234:237], v[186:189]
	v_mfma_f32_16x16x32_bf16 v[182:185], v[124:127], v[234:237], v[182:185]
	v_mfma_f32_16x16x32_bf16 v[178:181], v[128:131], v[234:237], v[178:181]
	v_mfma_f32_16x16x32_bf16 v[174:177], v[116:119], v[238:241], v[174:177]
	v_mfma_f32_16x16x32_bf16 v[170:173], v[120:123], v[238:241], v[170:173]
	v_mfma_f32_16x16x32_bf16 v[166:169], v[124:127], v[238:241], v[166:169]
	v_mfma_f32_16x16x32_bf16 v[162:165], v[128:131], v[238:241], v[162:165]
	ds_read_b128 v[94:97], v244
	ds_read_b128 v[98:101], v244 offset:2048
	ds_read_b128 v[102:105], v244 offset:4096
	ds_read_b128 v[106:109], v244 offset:6144
	ds_read_b128 v[116:119], v245 offset:49152
	ds_read_b128 v[120:123], v245 offset:51200
	ds_read_b128 v[124:127], v245 offset:53248
	ds_read_b128 v[128:131], v245 offset:55296
	ds_read_b128 v[226:229], v244 offset:32768
	ds_read_b128 v[230:233], v244 offset:34816
	ds_read_b128 v[234:237], v244 offset:36864
	ds_read_b128 v[238:241], v244 offset:38912
	s_waitcnt lgkmcnt(0)
	s_barrier
	s_cmpk_eq_i32 s0, 0x1580
	s_cbranch_scc1 .Lffo4_noa
	s_mov_b32 m0, s21
	v_lshl_add_u64 v[82:83], v[74:75], 0, s[0:1]
	global_load_lds_dwordx4 v[82:83], off
	s_add_i32 m0, m0, 0x1000
	v_lshl_add_u64 v[84:85], v[76:77], 0, s[0:1]
	global_load_lds_dwordx4 v[84:85], off
	s_add_i32 m0, m0, 0x1000
	v_lshl_add_u64 v[82:83], v[78:79], 0, s[0:1]
	global_load_lds_dwordx4 v[82:83], off
	s_add_i32 m0, m0, 0x1000
	v_lshl_add_u64 v[84:85], v[80:81], 0, s[0:1]
	global_load_lds_dwordx4 v[84:85], off
	s_add_i32 m0, m0, 0x1000
	s_add_u32 s20, s0, 0xb0000
	s_add_i32 m0, s21, 0x8000
	v_add_co_u32_e32 v82, vcc, s20, v74
	v_addc_co_u32_e32 v83, vcc, 0, v75, vcc
	global_load_lds_dwordx4 v[82:83], off
	s_add_i32 m0, m0, 0x1000
	v_add_co_u32_e32 v84, vcc, s20, v76
	v_addc_co_u32_e32 v85, vcc, 0, v77, vcc
	global_load_lds_dwordx4 v[84:85], off
	s_add_i32 m0, m0, 0x1000
	v_add_co_u32_e32 v82, vcc, s20, v78
	v_addc_co_u32_e32 v83, vcc, 0, v79, vcc
	global_load_lds_dwordx4 v[82:83], off
	s_add_i32 m0, m0, 0x1000
	v_add_co_u32_e32 v84, vcc, s20, v80
	v_addc_co_u32_e32 v85, vcc, 0, v81, vcc
	global_load_lds_dwordx4 v[84:85], off
; template <class Epi>
; DI void gemm_tile(const bf16_t* __restrict__ A, int lda, const bf16_t* __restrict__ Bt, int ldb, int K, int row0, int col0, char* lds, const Epi& epi) {
;     ...
;   epi(acc, row0 + wr * 64, col0 + wc * 64, fr, fq);
;   DI void operator()(const f32x4 (&acc)[4][4], int r0, int c0, int fr, int fq) const {
; #pragma unroll
;     for (int m = 0; m < 4; ++m) {
;       const int row = r0 + m * 16 + fr; const int b = row / TB, s = row % TB;
;       const float* src = xsrc_row(*p, from_inputs, b, s);
;       float* dst = xdst_row(*p, b, s);
;       const float* gate = p->MOD + (size_t)(l * 9 + (s < NCTX ? 8 : b)) * 6144 + gate_off;
; #pragma unroll
;       for (int n = 0; n < 4; ++n) {
;         const int col = c0 + n * 16 + fq * 4;
;         f32x4 g = *(const f32x4*)(gate + col), xv = *(const f32x4*)(src + col);
;         *(f32x4*)(dst + col) = xv + g * acc[m][n];
;       }
;     }
;   }
.Lffo4_noa:
	v_mfma_f32_16x16x32_bf16 v[62:65], v[116:119], v[94:97], v[62:65]
	v_mfma_f32_16x16x32_bf16 v[58:61], v[120:123], v[94:97], v[58:61]
	v_mfma_f32_16x16x32_bf16 v[54:57], v[124:127], v[94:97], v[54:57]
	v_mfma_f32_16x16x32_bf16 v[50:53], v[128:131], v[94:97], v[50:53]
	v_mfma_f32_16x16x32_bf16 v[46:49], v[116:119], v[98:101], v[46:49]
	v_mfma_f32_16x16x32_bf16 v[42:45], v[120:123], v[98:101], v[42:45]
	v_mfma_f32_16x16x32_bf16 v[38:41], v[124:127], v[98:101], v[38:41]
	v_mfma_f32_16x16x32_bf16 v[34:37], v[128:131], v[98:101], v[34:37]
	v_mfma_f32_16x16x32_bf16 v[30:33], v[116:119], v[102:105], v[30:33]
	v_mfma_f32_16x16x32_bf16 v[26:29], v[120:123], v[102:105], v[26:29]
	v_mfma_f32_16x16x32_bf16 v[22:25], v[124:127], v[102:105], v[22:25]
	v_mfma_f32_16x16x32_bf16 v[18:21], v[128:131], v[102:105], v[18:21]
	v_mfma_f32_16x16x32_bf16 v[14:17], v[116:119], v[106:109], v[14:17]
	v_mfma_f32_16x16x32_bf16 v[10:13], v[120:123], v[106:109], v[10:13]
	v_mfma_f32_16x16x32_bf16 v[6:9], v[124:127], v[106:109], v[6:9]
	v_mfma_f32_16x16x32_bf16 v[2:5], v[128:131], v[106:109], v[2:5]
	v_mfma_f32_16x16x32_bf16 v[222:225], v[116:119], v[226:229], v[222:225]
	v_mfma_f32_16x16x32_bf16 v[218:221], v[120:123], v[226:229], v[218:221]
	v_mfma_f32_16x16x32_bf16 v[214:217], v[124:127], v[226:229], v[214:217]
	v_mfma_f32_16x16x32_bf16 v[210:213], v[128:131], v[226:229], v[210:213]
	v_mfma_f32_16x16x32_bf16 v[206:209], v[116:119], v[230:233], v[206:209]
	v_mfma_f32_16x16x32_bf16 v[202:205], v[120:123], v[230:233], v[202:205]
	v_mfma_f32_16x16x32_bf16 v[198:201], v[124:127], v[230:233], v[198:201]
	v_mfma_f32_16x16x32_bf16 v[194:197], v[128:131], v[230:233], v[194:197]
	v_mfma_f32_16x16x32_bf16 v[190:193], v[116:119], v[234:237], v[190:193]
	v_mfma_f32_16x16x32_bf16 v[186:189], v[120:123], v[234:237], v[186:189]
	v_mfma_f32_16x16x32_bf16 v[182:185], v[124:127], v[234:237], v[182:185]
	v_mfma_f32_16x16x32_bf16 v[178:181], v[128:131], v[234:237], v[178:181]
	v_mfma_f32_16x16x32_bf16 v[174:177], v[116:119], v[238:241], v[174:177]
	v_mfma_f32_16x16x32_bf16 v[170:173], v[120:123], v[238:241], v[170:173]
	v_mfma_f32_16x16x32_bf16 v[166:169], v[124:127], v[238:241], v[166:169]
	v_mfma_f32_16x16x32_bf16 v[162:165], v[128:131], v[238:241], v[162:165]
	s_add_u32 s0, s0, 0x80
	s_cmpk_lg_i32 s0, 0x1600
	s_cbranch_scc1 .LBB0_84
	v_lshlrev_b32_e32 v1, 6, v1
	v_lshlrev_b32_e32 v67, 2, v86
	v_or3_b32 v80, v1, v67, s2
	v_lshlrev_b32_e32 v66, 2, v80
	v_mov_b32_e32 v67, 0
	v_mov_b32_e32 v100, s64
	v_mov_b32_e32 v101, s65
	v_mov_b32_e32 v102, s56
	v_mov_b32_e32 v103, s57
	s_add_u32 s0, s58, 0x5000
	s_addc_u32 s1, s59, 0
	v_mov_b32_e32 v108, s0
	v_mov_b32_e32 v109, s1
	v_mov_b32_e32 v110, 8
	v_or_b32_e32 v74, s3, v87
	v_lshl_add_u32 v74, v88, 6, v74
	v_mov_b32_e32 v88, v74
	v_mul_hi_i32 v89, v88, s47
	v_lshrrev_b32_e32 v90, 31, v89
	v_ashrrev_i32_e32 v89, 9, v89
	v_add_u32_e32 v91, v89, v90
	v_mul_i32_i24_e32 v89, 0x900, v91
	v_sub_u32_e32 v92, v88, v89
	v_cmp_lt_i32_e32 vcc, s33, v92
	v_lshlrev_b32_e32 v89, 11, v91
	v_add3_u32 v89, v92, v89, s75
	v_lshl_add_u32 v90, v91, 8, v92
	v_cndmask_b32_e32 v94, v90, v89, vcc
	v_ashrrev_i32_e32 v95, 31, v94
	v_lshlrev_b64 v[96:97], 12, v[94:95]
	v_lshl_add_u64 v[96:97], v[96:97], 0, v[66:67]
	v_cndmask_b32_e32 v98, v100, v102, vcc
	v_cndmask_b32_e32 v99, v101, v103, vcc
	v_lshl_add_u64 v[82:83], v[98:99], 0, v[96:97]
	v_cndmask_b32_e32 v93, v110, v91, vcc
	v_add_u32_e32 v93, s82, v93
	v_mad_i64_i32 v[76:77], s[0:1], v93, s24, v[108:109]
	s_nop 0
	v_lshl_add_u64 v[76:77], v[76:77], 0, v[66:67]
	global_load_dwordx4 v[116:119], v[76:77], off
	global_load_dwordx4 v[120:123], v[76:77], off offset:64
	global_load_dwordx4 v[124:127], v[76:77], off offset:128
	global_load_dwordx4 v[128:131], v[76:77], off offset:192
	global_load_dwordx4 v[226:229], v[82:83], off
	global_load_dwordx4 v[230:233], v[82:83], off offset:64
	global_load_dwordx4 v[234:237], v[82:83], off offset:128
	global_load_dwordx4 v[238:241], v[82:83], off offset:192
	v_or_b32_e32 v88, 16, v74
	v_mul_hi_i32 v89, v88, s47
	v_lshrrev_b32_e32 v90, 31, v89
	v_ashrrev_i32_e32 v89, 9, v89
	v_add_u32_e32 v91, v89, v90
	v_mul_i32_i24_e32 v89, 0x900, v91
	v_sub_u32_e32 v92, v88, v89
	v_cmp_lt_i32_e32 vcc, s33, v92
	v_lshlrev_b32_e32 v89, 11, v91
	v_add3_u32 v89, v92, v89, s75
	v_lshl_add_u32 v90, v91, 8, v92
	v_cndmask_b32_e32 v94, v90, v89, vcc
	v_ashrrev_i32_e32 v95, 31, v94
	v_lshlrev_b64 v[96:97], 12, v[94:95]
	v_lshl_add_u64 v[96:97], v[96:97], 0, v[66:67]
	v_cndmask_b32_e32 v98, v100, v102, vcc
	v_cndmask_b32_e32 v99, v101, v103, vcc
	v_lshl_add_u64 v[84:85], v[98:99], 0, v[96:97]
	global_load_dwordx4 v[242:245], v[84:85], off
	global_load_dwordx4 v[246:249], v[84:85], off offset:64
	global_load_dwordx4 v[132:135], v[84:85], off offset:128
	global_load_dwordx4 v[68:71], v[84:85], off offset:192
	s_waitcnt vmcnt(7)
	v_pk_fma_f32 v[64:65], v[64:65], v[118:119], v[228:229]
	v_pk_fma_f32 v[62:63], v[62:63], v[116:117], v[226:227]
	global_store_dwordx4 v[82:83], v[62:65], off
	s_waitcnt vmcnt(7)
	v_pk_fma_f32 v[60:61], v[60:61], v[122:123], v[232:233]
	v_pk_fma_f32 v[58:59], v[58:59], v[120:121], v[230:231]
	global_store_dwordx4 v[82:83], v[58:61], off offset:64
	s_waitcnt vmcnt(7)
	v_pk_fma_f32 v[56:57], v[56:57], v[126:127], v[236:237]
	v_pk_fma_f32 v[54:55], v[54:55], v[124:125], v[234:235]
	global_store_dwordx4 v[82:83], v[54:57], off offset:128
	s_waitcnt vmcnt(7)
	v_pk_fma_f32 v[52:53], v[52:53], v[130:131], v[240:241]
	v_pk_fma_f32 v[50:51], v[50:51], v[128:129], v[238:239]
	global_store_dwordx4 v[82:83], v[50:53], off offset:192
	s_waitcnt vmcnt(7)
;   DI void operator()(const f32x4 (&acc)[4][4], int r0, int c0, int fr, int fq) const {
; #pragma unroll
;     for (int m = 0; m < 4; ++m) {
;       const int row = r0 + m * 16 + fr; const int b = row / TB, s = row % TB;
;       const float* src = xsrc_row(*p, from_inputs, b, s);
;       float* dst = xdst_row(*p, b, s);
;       const float* gate = p->MOD + (size_t)(l * 9 + (s < NCTX ? 8 : b)) * 6144 + gate_off;
; #pragma unroll
;       for (int n = 0; n < 4; ++n) {
;         const int col = c0 + n * 16 + fq * 4;
;         f32x4 g = *(const f32x4*)(gate + col), xv = *(const f32x4*)(src + col);
;         *(f32x4*)(dst + col) = xv + g * acc[m][n];
;       }
;     }
	v_pk_fma_f32 v[48:49], v[48:49], v[118:119], v[244:245]
	v_pk_fma_f32 v[46:47], v[46:47], v[116:117], v[242:243]
	global_store_dwordx4 v[84:85], v[46:49], off
	s_waitcnt vmcnt(7)
	v_pk_fma_f32 v[44:45], v[44:45], v[122:123], v[248:249]
	v_pk_fma_f32 v[42:43], v[42:43], v[120:121], v[246:247]
	global_store_dwordx4 v[84:85], v[42:45], off offset:64
	s_waitcnt vmcnt(7)
	v_pk_fma_f32 v[40:41], v[40:41], v[126:127], v[134:135]
	v_pk_fma_f32 v[38:39], v[38:39], v[124:125], v[132:133]
	global_store_dwordx4 v[84:85], v[38:41], off offset:128
	s_waitcnt vmcnt(7)
	v_pk_fma_f32 v[36:37], v[36:37], v[130:131], v[70:71]
	v_pk_fma_f32 v[34:35], v[34:35], v[128:129], v[68:69]
	global_store_dwordx4 v[84:85], v[34:37], off offset:192
	v_or_b32_e32 v88, 32, v74
	v_mul_hi_i32 v89, v88, s47
	v_lshrrev_b32_e32 v90, 31, v89
	v_ashrrev_i32_e32 v89, 9, v89
	v_add_u32_e32 v91, v89, v90
	v_mul_i32_i24_e32 v89, 0x900, v91
	v_sub_u32_e32 v92, v88, v89
	v_cmp_lt_i32_e32 vcc, s33, v92
	v_lshlrev_b32_e32 v89, 11, v91
	v_add3_u32 v89, v92, v89, s75
	v_lshl_add_u32 v90, v91, 8, v92
	v_cndmask_b32_e32 v94, v90, v89, vcc
	v_ashrrev_i32_e32 v95, 31, v94
	v_lshlrev_b64 v[96:97], 12, v[94:95]
	v_lshl_add_u64 v[96:97], v[96:97], 0, v[66:67]
	v_cndmask_b32_e32 v98, v100, v102, vcc
	v_cndmask_b32_e32 v99, v101, v103, vcc
	v_lshl_add_u64 v[82:83], v[98:99], 0, v[96:97]
	global_load_dwordx4 v[226:229], v[82:83], off
	global_load_dwordx4 v[230:233], v[82:83], off offset:64
	global_load_dwordx4 v[234:237], v[82:83], off offset:128
	global_load_dwordx4 v[238:241], v[82:83], off offset:192
	v_or_b32_e32 v88, 48, v74
	v_mul_hi_i32 v89, v88, s47
	v_lshrrev_b32_e32 v90, 31, v89
	v_ashrrev_i32_e32 v89, 9, v89
	v_add_u32_e32 v91, v89, v90
	v_mul_i32_i24_e32 v89, 0x900, v91
	v_sub_u32_e32 v92, v88, v89
	v_cmp_lt_i32_e32 vcc, s33, v92
	v_lshlrev_b32_e32 v89, 11, v91
	v_add3_u32 v89, v92, v89, s75
	v_lshl_add_u32 v90, v91, 8, v92
	v_cndmask_b32_e32 v94, v90, v89, vcc
	v_ashrrev_i32_e32 v95, 31, v94
	v_lshlrev_b64 v[96:97], 12, v[94:95]
	v_lshl_add_u64 v[96:97], v[96:97], 0, v[66:67]
	v_cndmask_b32_e32 v98, v100, v102, vcc
	v_cndmask_b32_e32 v99, v101, v103, vcc
	v_lshl_add_u64 v[84:85], v[98:99], 0, v[96:97]
	global_load_dwordx4 v[242:245], v[84:85], off
	global_load_dwordx4 v[246:249], v[84:85], off offset:64
	global_load_dwordx4 v[132:135], v[84:85], off offset:128
	global_load_dwordx4 v[68:71], v[84:85], off offset:192
	s_waitcnt vmcnt(7)
	v_pk_fma_f32 v[32:33], v[32:33], v[118:119], v[228:229]
	v_pk_fma_f32 v[30:31], v[30:31], v[116:117], v[226:227]
	global_store_dwordx4 v[82:83], v[30:33], off
	s_waitcnt vmcnt(7)
	v_pk_fma_f32 v[28:29], v[28:29], v[122:123], v[232:233]
	v_pk_fma_f32 v[26:27], v[26:27], v[120:121], v[230:231]
	global_store_dwordx4 v[82:83], v[26:29], off offset:64
	s_waitcnt vmcnt(7)
	v_pk_fma_f32 v[24:25], v[24:25], v[126:127], v[236:237]
	v_pk_fma_f32 v[22:23], v[22:23], v[124:125], v[234:235]
	global_store_dwordx4 v[82:83], v[22:25], off offset:128
	s_waitcnt vmcnt(7)
	v_pk_fma_f32 v[20:21], v[20:21], v[130:131], v[240:241]
	v_pk_fma_f32 v[18:19], v[18:19], v[128:129], v[238:239]
	global_store_dwordx4 v[82:83], v[18:21], off offset:192
	s_waitcnt vmcnt(7)
	v_pk_fma_f32 v[16:17], v[16:17], v[118:119], v[244:245]
	v_pk_fma_f32 v[14:15], v[14:15], v[116:117], v[242:243]
	global_store_dwordx4 v[84:85], v[14:17], off
	s_waitcnt vmcnt(7)
	v_pk_fma_f32 v[12:13], v[12:13], v[122:123], v[248:249]
	v_pk_fma_f32 v[10:11], v[10:11], v[120:121], v[246:247]
	global_store_dwordx4 v[84:85], v[10:13], off offset:64
	s_waitcnt vmcnt(7)
	v_pk_fma_f32 v[8:9], v[8:9], v[126:127], v[134:135]
	v_pk_fma_f32 v[6:7], v[6:7], v[124:125], v[132:133]
	global_store_dwordx4 v[84:85], v[6:9], off offset:128
	s_waitcnt vmcnt(7)
	v_pk_fma_f32 v[4:5], v[4:5], v[130:131], v[70:71]
	v_pk_fma_f32 v[2:3], v[2:3], v[128:129], v[68:69]
	global_store_dwordx4 v[84:85], v[2:5], off offset:192
	s_nop 3
	v_mov_b32_e32 v65, v225
	v_mov_b32_e32 v64, v224
	v_mov_b32_e32 v63, v223
	v_mov_b32_e32 v62, v222
	v_mov_b32_e32 v61, v221
	v_mov_b32_e32 v60, v220
	v_mov_b32_e32 v59, v219
	v_mov_b32_e32 v58, v218
	v_mov_b32_e32 v57, v217
	v_mov_b32_e32 v56, v216
	v_mov_b32_e32 v55, v215
	v_mov_b32_e32 v54, v214
	v_mov_b32_e32 v53, v213
	v_mov_b32_e32 v52, v212
	v_mov_b32_e32 v51, v211
	v_mov_b32_e32 v50, v210
	v_mov_b32_e32 v49, v209
	v_mov_b32_e32 v48, v208
	v_mov_b32_e32 v47, v207
	v_mov_b32_e32 v46, v206
	v_mov_b32_e32 v45, v205
	v_mov_b32_e32 v44, v204
	v_mov_b32_e32 v43, v203
	v_mov_b32_e32 v42, v202
	v_mov_b32_e32 v41, v201
	v_mov_b32_e32 v40, v200
	v_mov_b32_e32 v39, v199
	v_mov_b32_e32 v38, v198
	v_mov_b32_e32 v37, v197
	v_mov_b32_e32 v36, v196
	v_mov_b32_e32 v35, v195
	v_mov_b32_e32 v34, v194
	v_mov_b32_e32 v33, v193
	v_mov_b32_e32 v32, v192
	v_mov_b32_e32 v31, v191
	v_mov_b32_e32 v30, v190
	v_mov_b32_e32 v29, v189
	v_mov_b32_e32 v28, v188
	v_mov_b32_e32 v27, v187
	v_mov_b32_e32 v26, v186
	v_mov_b32_e32 v25, v185
	v_mov_b32_e32 v24, v184
	v_mov_b32_e32 v23, v183
	v_mov_b32_e32 v22, v182
	v_mov_b32_e32 v21, v181
	v_mov_b32_e32 v20, v180
	v_mov_b32_e32 v19, v179
	v_mov_b32_e32 v18, v178
	v_mov_b32_e32 v17, v177
	v_mov_b32_e32 v16, v176
	v_mov_b32_e32 v15, v175
	v_mov_b32_e32 v14, v174
	v_mov_b32_e32 v13, v173
	v_mov_b32_e32 v12, v172
	v_mov_b32_e32 v11, v171
	v_mov_b32_e32 v10, v170
	v_mov_b32_e32 v9, v169
	v_mov_b32_e32 v8, v168
	v_mov_b32_e32 v7, v167
	v_mov_b32_e32 v6, v166
	v_mov_b32_e32 v5, v165
	v_mov_b32_e32 v4, v164
	v_mov_b32_e32 v3, v163
	v_mov_b32_e32 v2, v162
	v_add_u32_e32 v74, 0x80, v74
	v_mov_b32_e32 v88, v74
	v_mul_hi_i32 v89, v88, s47
	v_lshrrev_b32_e32 v90, 31, v89
	v_ashrrev_i32_e32 v89, 9, v89
;   DI void operator()(const f32x4 (&acc)[4][4], int r0, int c0, int fr, int fq) const {
; #pragma unroll
;     for (int m = 0; m < 4; ++m) {
;       const int row = r0 + m * 16 + fr; const int b = row / TB, s = row % TB;
;       const float* src = xsrc_row(*p, from_inputs, b, s);
;       float* dst = xdst_row(*p, b, s);
;       const float* gate = p->MOD + (size_t)(l * 9 + (s < NCTX ? 8 : b)) * 6144 + gate_off;
; #pragma unroll
;       for (int n = 0; n < 4; ++n) {
;         const int col = c0 + n * 16 + fq * 4;
;         f32x4 g = *(const f32x4*)(gate + col), xv = *(const f32x4*)(src + col);
;         *(f32x4*)(dst + col) = xv + g * acc[m][n];
;       }
;     }
	v_add_u32_e32 v91, v89, v90
	v_mul_i32_i24_e32 v89, 0x900, v91
	v_sub_u32_e32 v92, v88, v89
	v_cmp_lt_i32_e32 vcc, s33, v92
	v_lshlrev_b32_e32 v89, 11, v91
	v_add3_u32 v89, v92, v89, s75
	v_lshl_add_u32 v90, v91, 8, v92
	v_cndmask_b32_e32 v94, v90, v89, vcc
	v_ashrrev_i32_e32 v95, 31, v94
	v_lshlrev_b64 v[96:97], 12, v[94:95]
	v_lshl_add_u64 v[96:97], v[96:97], 0, v[66:67]
	v_cndmask_b32_e32 v98, v100, v102, vcc
	v_cndmask_b32_e32 v99, v101, v103, vcc
	v_lshl_add_u64 v[82:83], v[98:99], 0, v[96:97]
	v_cndmask_b32_e32 v93, v110, v91, vcc
	v_add_u32_e32 v93, s82, v93
	v_mad_i64_i32 v[76:77], s[0:1], v93, s24, v[108:109]
	s_nop 0
	v_lshl_add_u64 v[76:77], v[76:77], 0, v[66:67]
	global_load_dwordx4 v[116:119], v[76:77], off
	global_load_dwordx4 v[120:123], v[76:77], off offset:64
	global_load_dwordx4 v[124:127], v[76:77], off offset:128
	global_load_dwordx4 v[128:131], v[76:77], off offset:192
	global_load_dwordx4 v[226:229], v[82:83], off
	global_load_dwordx4 v[230:233], v[82:83], off offset:64
	global_load_dwordx4 v[234:237], v[82:83], off offset:128
	global_load_dwordx4 v[238:241], v[82:83], off offset:192
	v_or_b32_e32 v88, 16, v74
	v_mul_hi_i32 v89, v88, s47
	v_lshrrev_b32_e32 v90, 31, v89
	v_ashrrev_i32_e32 v89, 9, v89
	v_add_u32_e32 v91, v89, v90
	v_mul_i32_i24_e32 v89, 0x900, v91
	v_sub_u32_e32 v92, v88, v89
	v_cmp_lt_i32_e32 vcc, s33, v92
	v_lshlrev_b32_e32 v89, 11, v91
	v_add3_u32 v89, v92, v89, s75
	v_lshl_add_u32 v90, v91, 8, v92
	v_cndmask_b32_e32 v94, v90, v89, vcc
	v_ashrrev_i32_e32 v95, 31, v94
	v_lshlrev_b64 v[96:97], 12, v[94:95]
	v_lshl_add_u64 v[96:97], v[96:97], 0, v[66:67]
	v_cndmask_b32_e32 v98, v100, v102, vcc
	v_cndmask_b32_e32 v99, v101, v103, vcc
	v_lshl_add_u64 v[84:85], v[98:99], 0, v[96:97]
	global_load_dwordx4 v[242:245], v[84:85], off
	global_load_dwordx4 v[246:249], v[84:85], off offset:64
	global_load_dwordx4 v[132:135], v[84:85], off offset:128
	global_load_dwordx4 v[68:71], v[84:85], off offset:192
	s_waitcnt vmcnt(7)
	v_pk_fma_f32 v[64:65], v[64:65], v[118:119], v[228:229]
	v_pk_fma_f32 v[62:63], v[62:63], v[116:117], v[226:227]
	global_store_dwordx4 v[82:83], v[62:65], off
	s_waitcnt vmcnt(7)
	v_pk_fma_f32 v[60:61], v[60:61], v[122:123], v[232:233]
	v_pk_fma_f32 v[58:59], v[58:59], v[120:121], v[230:231]
	global_store_dwordx4 v[82:83], v[58:61], off offset:64
	s_waitcnt vmcnt(7)
	v_pk_fma_f32 v[56:57], v[56:57], v[126:127], v[236:237]
	v_pk_fma_f32 v[54:55], v[54:55], v[124:125], v[234:235]
	global_store_dwordx4 v[82:83], v[54:57], off offset:128
	s_waitcnt vmcnt(7)
	v_pk_fma_f32 v[52:53], v[52:53], v[130:131], v[240:241]
	v_pk_fma_f32 v[50:51], v[50:51], v[128:129], v[238:239]
	global_store_dwordx4 v[82:83], v[50:53], off offset:192
	s_waitcnt vmcnt(7)
	v_pk_fma_f32 v[48:49], v[48:49], v[118:119], v[244:245]
	v_pk_fma_f32 v[46:47], v[46:47], v[116:117], v[242:243]
	global_store_dwordx4 v[84:85], v[46:49], off
	s_waitcnt vmcnt(7)
	v_pk_fma_f32 v[44:45], v[44:45], v[122:123], v[248:249]
	v_pk_fma_f32 v[42:43], v[42:43], v[120:121], v[246:247]
	global_store_dwordx4 v[84:85], v[42:45], off offset:64
	s_waitcnt vmcnt(7)
	v_pk_fma_f32 v[40:41], v[40:41], v[126:127], v[134:135]
	v_pk_fma_f32 v[38:39], v[38:39], v[124:125], v[132:133]
	global_store_dwordx4 v[84:85], v[38:41], off offset:128
	s_waitcnt vmcnt(7)
	v_pk_fma_f32 v[36:37], v[36:37], v[130:131], v[70:71]
	v_pk_fma_f32 v[34:35], v[34:35], v[128:129], v[68:69]
	global_store_dwordx4 v[84:85], v[34:37], off offset:192
	v_or_b32_e32 v88, 32, v74
	v_mul_hi_i32 v89, v88, s47
	v_lshrrev_b32_e32 v90, 31, v89
	v_ashrrev_i32_e32 v89, 9, v89
	v_add_u32_e32 v91, v89, v90
	v_mul_i32_i24_e32 v89, 0x900, v91
	v_sub_u32_e32 v92, v88, v89
	v_cmp_lt_i32_e32 vcc, s33, v92
	v_lshlrev_b32_e32 v89, 11, v91
	v_add3_u32 v89, v92, v89, s75
	v_lshl_add_u32 v90, v91, 8, v92
	v_cndmask_b32_e32 v94, v90, v89, vcc
	v_ashrrev_i32_e32 v95, 31, v94
	v_lshlrev_b64 v[96:97], 12, v[94:95]
	v_lshl_add_u64 v[96:97], v[96:97], 0, v[66:67]
	v_cndmask_b32_e32 v98, v100, v102, vcc
	v_cndmask_b32_e32 v99, v101, v103, vcc
	v_lshl_add_u64 v[82:83], v[98:99], 0, v[96:97]
	global_load_dwordx4 v[226:229], v[82:83], off
	global_load_dwordx4 v[230:233], v[82:83], off offset:64
	global_load_dwordx4 v[234:237], v[82:83], off offset:128
	global_load_dwordx4 v[238:241], v[82:83], off offset:192
	v_or_b32_e32 v88, 48, v74
	v_mul_hi_i32 v89, v88, s47
	v_lshrrev_b32_e32 v90, 31, v89
	v_ashrrev_i32_e32 v89, 9, v89
	v_add_u32_e32 v91, v89, v90
	v_mul_i32_i24_e32 v89, 0x900, v91
	v_sub_u32_e32 v92, v88, v89
	v_cmp_lt_i32_e32 vcc, s33, v92
	v_lshlrev_b32_e32 v89, 11, v91
	v_add3_u32 v89, v92, v89, s75
	v_lshl_add_u32 v90, v91, 8, v92
	v_cndmask_b32_e32 v94, v90, v89, vcc
	v_ashrrev_i32_e32 v95, 31, v94
	v_lshlrev_b64 v[96:97], 12, v[94:95]
	v_lshl_add_u64 v[96:97], v[96:97], 0, v[66:67]
	v_cndmask_b32_e32 v98, v100, v102, vcc
	v_cndmask_b32_e32 v99, v101, v103, vcc
	v_lshl_add_u64 v[84:85], v[98:99], 0, v[96:97]
	global_load_dwordx4 v[242:245], v[84:85], off
	global_load_dwordx4 v[246:249], v[84:85], off offset:64
	global_load_dwordx4 v[132:135], v[84:85], off offset:128
	global_load_dwordx4 v[68:71], v[84:85], off offset:192
	s_waitcnt vmcnt(7)
	v_pk_fma_f32 v[32:33], v[32:33], v[118:119], v[228:229]
	v_pk_fma_f32 v[30:31], v[30:31], v[116:117], v[226:227]
	global_store_dwordx4 v[82:83], v[30:33], off
	s_waitcnt vmcnt(7)
	v_pk_fma_f32 v[28:29], v[28:29], v[122:123], v[232:233]
	v_pk_fma_f32 v[26:27], v[26:27], v[120:121], v[230:231]
	global_store_dwordx4 v[82:83], v[26:29], off offset:64
	s_waitcnt vmcnt(7)
	v_pk_fma_f32 v[24:25], v[24:25], v[126:127], v[236:237]
	v_pk_fma_f32 v[22:23], v[22:23], v[124:125], v[234:235]
	global_store_dwordx4 v[82:83], v[22:25], off offset:128
	s_waitcnt vmcnt(7)
	v_pk_fma_f32 v[20:21], v[20:21], v[130:131], v[240:241]
	v_pk_fma_f32 v[18:19], v[18:19], v[128:129], v[238:239]
	global_store_dwordx4 v[82:83], v[18:21], off offset:192
	s_waitcnt vmcnt(7)
	v_pk_fma_f32 v[16:17], v[16:17], v[118:119], v[244:245]
	v_pk_fma_f32 v[14:15], v[14:15], v[116:117], v[242:243]
	global_store_dwordx4 v[84:85], v[14:17], off
	s_waitcnt vmcnt(7)
	v_pk_fma_f32 v[12:13], v[12:13], v[122:123], v[248:249]
	v_pk_fma_f32 v[10:11], v[10:11], v[120:121], v[246:247]
	global_store_dwordx4 v[84:85], v[10:13], off offset:64
	s_waitcnt vmcnt(7)
	v_pk_fma_f32 v[8:9], v[8:9], v[126:127], v[134:135]
	v_pk_fma_f32 v[6:7], v[6:7], v[124:125], v[132:133]
	global_store_dwordx4 v[84:85], v[6:9], off offset:128
	s_waitcnt vmcnt(7)
	v_pk_fma_f32 v[4:5], v[4:5], v[130:131], v[70:71]
	v_pk_fma_f32 v[2:3], v[2:3], v[128:129], v[68:69]
	global_store_dwordx4 v[84:85], v[2:5], off offset:192
	s_add_i32 s27, s27, 1
	s_mov_b64 s[0:1], 0
	s_branch .LBB0_71
